# sample-attention unit prologue: query-image loads issued together, one wait, then LDS writes
# baseline (speedup 1.0000x reference)
; #define LAS __attribute__((address_space(3)))
; #define DAT_LD(p) __builtin_nontemporal_load(p)
; #define cache_lat KIN(2)
; #define cache_kr KIN(3)
; #define page_table ((const int*)karg(5))
; __device__ __forceinline__ void stage_load(Stage& s, const float* cache_lat, const float* cache_kr, const int pgv, int T, int kg, int w4, int lane) {
;     const int page = __builtin_amdgcn_readlane(pgv, T >> 1); const size_t key0 = (size_t)page * 128 + 64 * kg + 32 * (T & 1) + 8 * w4;
;     const float* lsrc = cache_lat + key0 * 256 + lane * 4;
; #pragma unroll
;     for (int j = 0; j < 8; ++j) s.lv[j] = DAT_LD((const f32x4*)(lsrc + j * 256));
;     s.kr = DAT_LD((const f32x4*)(cache_kr + (key0 + (lane >> 3)) * 32 + (lane & 7) * 4));
; __device__ __forceinline__ void unit(int b, int sp, const float* cache_lat, const float* cache_kr, const int* page_table, const bf16* QL, const bf16* Q, float* PO, float* PML, LAS unsigned char* lds, const int wid) {
;     int lane_; asm volatile("v_mbcnt_lo_u32_b32 %0, -1, 0\n\tv_mbcnt_hi_u32_b32 %0, -1, %0" : "=v"(lane_)); const int lane = lane_, tid = wid * 64 + lane, r32 = lane & 31, hi = lane >> 5;
;     const int kg = wid >> 2, w4 = wid & 3, qt = w4 >> 1, ch = w4 & 1;
;     const int pgv = (page_table + b * NPAGES + sp * PAGES)[lane & (PAGES - 1)];
;     Stage sA, sB;
;     stage_load(sA, cache_lat, cache_kr, pgv, 0, kg, w4, lane);
;     stage_load(sB, cache_lat, cache_kr, pgv, 1, kg, w4, lane);
;     for (int idx = tid; idx < 64 * 36; idx += NWAVES * 64) { const int row = idx / 36, c = idx - row * 36, s = row >> 3, h = row & 7;
;         const bf16* src = c < 32 ? QL + ((size_t)(b * 8 + s) * 2048 + h * 256 + c * 8) : Q + ((size_t)(NPR + b * 8 + s) * QW + h * 96 + 64 + (c - 32) * 8);
;         *(LAS v4u*)(lds + QIMG + row * PB + c * 16) = *(const v4u*)src; }
.LBB0_1032:
	s_and_b64 vcc, exec, s[10:11]
	s_cbranch_vccz .LBB0_1118
	s_lshr_b32 s3, s4, 2
	s_and_b32 s21, s4, 3
	s_mov_b64 s[4:5], s[0:1]
	s_load_dwordx2 s[10:11], s[4:5], 0x10
	s_mov_b64 s[4:5], s[0:1]
	s_load_dwordx2 s[12:13], s[4:5], 0x18
	s_mov_b64 s[4:5], s[0:1]
	s_load_dwordx2 s[4:5], s[4:5], 0x28
	s_mov_b64 s[52:53], s[0:1]
	s_mov_b64 s[50:51], s[0:1]
	s_mov_b64 s[24:25], s[0:1]
	s_load_dwordx2 s[46:47], s[24:25], 0xc8
	s_mov_b64 s[24:25], s[0:1]
	s_lshl_b32 s14, s3, 6
	s_load_dwordx2 s[48:49], s[24:25], 0xc8
	s_lshl_b64 s[24:25], s[14:15], 2
	s_waitcnt lgkmcnt(0)
	s_add_u32 s14, s4, s24
	s_addc_u32 s5, s5, s25
	s_lshl_b32 s4, s21, 6
	v_mbcnt_lo_u32_b32 v171, -1, 0
	v_mbcnt_hi_u32_b32 v171, -1, v171
	s_add_u32 s24, s14, s4
	v_and_b32_e32 v5, 15, v171
	s_addc_u32 s25, s5, 0
	v_lshlrev_b32_e32 v1, 2, v5
	global_load_dword v181, v1, s[24:25]
	v_lshlrev_b32_e32 v8, 2, v171
	v_ashrrev_i32_e32 v172, 3, v171
	v_ashrrev_i32_e32 v9, 31, v8
	v_ashrrev_i32_e32 v173, 31, v172
	v_lshlrev_b64 v[10:11], 2, v[8:9]
	v_and_b32_e32 v1, 28, v8
	v_mov_b32_e32 v7, v3
	v_lshlrev_b32_e32 v6, 2, v1
	v_readlane_b32 s5, v237, 4
	s_waitcnt vmcnt(0)
	v_readlane_b32 s24, v181, 0
	s_ashr_i32 s25, s24, 31
	s_lshl_b64 s[24:25], s[24:25], 7
	s_add_u32 s24, s24, s63
	s_addc_u32 s25, s25, 0
	s_lshl_b64 s[26:27], s[24:25], 10
	s_add_u32 s26, s10, s26
	v_lshl_add_u64 v[12:13], s[24:25], 0, v[172:173]
	s_addc_u32 s27, s11, s27
	s_or_b32 s24, s24, 32
	v_lshl_add_u64 v[14:15], s[26:27], 0, v[10:11]
	s_lshl_b64 s[26:27], s[24:25], 10
	v_lshlrev_b64 v[12:13], 7, v[12:13]
	v_lshl_add_u64 v[16:17], s[24:25], 0, v[172:173]
	s_add_u32 s24, s10, s26
	v_lshl_add_u64 v[12:13], s[12:13], 0, v[12:13]
	global_load_dwordx4 v[166:169], v[14:15], off nt
	global_load_dwordx4 v[158:161], v[14:15], off offset:1024 nt
	global_load_dwordx4 v[146:149], v[14:15], off offset:2048 nt
	global_load_dwordx4 v[138:141], v[14:15], off offset:3072 nt
	v_add_co_u32_e32 v14, vcc, s88, v14
	s_addc_u32 s25, s11, s27
	v_lshl_add_u64 v[12:13], v[12:13], 0, v[6:7]
	v_addc_co_u32_e32 v15, vcc, 0, v15, vcc
	v_lshl_add_u64 v[10:11], s[24:25], 0, v[10:11]
	global_load_dwordx4 v[110:113], v[12:13], off nt
	v_lshlrev_b64 v[12:13], 7, v[16:17]
	global_load_dwordx4 v[162:165], v[14:15], off nt
	global_load_dwordx4 v[154:157], v[14:15], off offset:1024 nt
	global_load_dwordx4 v[150:153], v[14:15], off offset:2048 nt
	global_load_dwordx4 v[142:145], v[14:15], off offset:3072 nt
	global_load_dwordx4 v[134:137], v[10:11], off nt
	global_load_dwordx4 v[130:133], v[10:11], off offset:1024 nt
	global_load_dwordx4 v[126:129], v[10:11], off offset:2048 nt
	global_load_dwordx4 v[118:121], v[10:11], off offset:3072 nt
	v_add_co_u32_e32 v10, vcc, 0x1000, v10
	v_lshl_add_u64 v[12:13], s[12:13], 0, v[12:13]
	s_nop 0
	v_addc_co_u32_e32 v11, vcc, 0, v11, vcc
	v_lshl_add_u64 v[12:13], v[12:13], 0, v[6:7]
	global_load_dwordx4 v[122:125], v[10:11], off nt
	global_load_dwordx4 v[114:117], v[10:11], off offset:1024 nt
	global_load_dwordx4 v[106:109], v[10:11], off offset:2048 nt
	global_load_dwordx4 v[102:105], v[10:11], off offset:3072 nt
	global_load_dwordx4 v[98:101], v[12:13], off nt
	v_add_u32_e32 v4, s5, v171
	s_movk_i32 s5, 0x900
	v_cmp_gt_i32_e32 vcc, s5, v4
	s_and_saveexec_b64 s[54:55], vcc
	s_cbranch_execz .LBB0_1040
	s_load_dwordx2 s[24:25], s[52:53], 0xc8
	s_nop 0
	s_load_dwordx2 s[50:51], s[50:51], 0xc8
	v_lshl_add_u32 v1, v171, 4, s85
	v_lshl_add_u32 v10, v171, 3, s82
	s_mov_b64 s[56:57], 0
	s_waitcnt lgkmcnt(0)
	s_add_u32 s52, s24, 0x1ac00000
	s_addc_u32 s53, s25, 0
	s_lshl_b32 s5, s3, 3
	s_add_i32 s14, s5, 0x8000
	s_branch .Lq0_head
.Lq0_head:
	s_mov_b32 s21, 0x38e38e39
	v_mul_hi_i32 v2, v4, s21
	v_lshrrev_b32_e32 v7, 31, v2
	v_ashrrev_i32_e32 v2, 3, v2
	v_add_u32_e32 v7, v2, v7
	s_movk_i32 s21, 0xffdc
	v_mad_u64_u32 v[12:13], s[24:25], v7, s21, v[4:5]
	v_ashrrev_i32_e32 v11, 3, v7
	s_movk_i32 s21, 0xfee0
	v_and_b32_e32 v2, 7, v7
	v_cmp_lt_i32_e32 vcc, 31, v12
	v_mad_u64_u32 v[12:13], s[24:25], v7, s21, v[10:11]
	s_and_saveexec_b64 s[24:25], vcc
	s_xor_b64 s[58:59], exec, s[24:25]
	s_cbranch_execz .Lq0_else
	v_add_u32_e32 v11, s14, v11
	v_mul_u32_u24_e32 v14, 0x60, v2
	v_add_u32_e32 v2, 0xffffff00, v12
	v_mov_b64_e32 v[12:13], s[50:51]
	v_mad_i64_i32 v[12:13], s[24:25], v11, s87, v[12:13]
	v_lshlrev_b32_e32 v14, 1, v14
	v_mov_b32_e32 v15, v3
	v_lshl_add_u64 v[12:13], v[12:13], 0, v[14:15]
	v_lshl_add_u64 v[12:13], v[2:3], 1, v[12:13]
	s_mov_b64 s[24:25], 0x13a00080
	v_lshl_add_u64 v[14:15], v[12:13], 0, s[24:25]

; #define LAS __attribute__((address_space(3)))
; __device__ __forceinline__ void unit(int b, int sp, const float* cache_lat, const float* cache_kr, const int* page_table, const bf16* QL, const bf16* Q, float* PO, float* PML, LAS unsigned char* lds, const int wid) {
;     ...
;     for (int idx = tid; idx < 64 * 36; idx += NWAVES * 64) { const int row = idx / 36, c = idx - row * 36, s = row >> 3, h = row & 7;
;         const bf16* src = c < 32 ? QL + ((size_t)(b * 8 + s) * 2048 + h * 256 + c * 8) : Q + ((size_t)(NPR + b * 8 + s) * QW + h * 96 + 64 + (c - 32) * 8);
;         *(LAS v4u*)(lds + QIMG + row * PB + c * 16) = *(const v4u*)src; }
.Lq0_join:
	s_or_b64 exec, exec, s[58:59]
	global_load_dwordx4 v[214:217], v[14:15], off
	s_movk_i32 s21, 0x6ff
	v_lshl_add_u32 v242, v7, 4, v1
	v_add_u32_e32 v7, 0x200, v4
	v_cmp_lt_i32_e32 vcc, s21, v4
	v_add_u32_e32 v1, 0x2000, v1
	v_add_u32_e32 v10, 0x1000, v10
	s_or_b64 s[56:57], vcc, s[56:57]
	v_mov_b32_e32 v4, v7

; #define LAS __attribute__((address_space(3)))
; __device__ __forceinline__ void unit(int b, int sp, const float* cache_lat, const float* cache_kr, const int* page_table, const bf16* QL, const bf16* Q, float* PO, float* PML, LAS unsigned char* lds, const int wid) {
;     ...
;     for (int idx = tid; idx < 64 * 36; idx += NWAVES * 64) { const int row = idx / 36, c = idx - row * 36, s = row >> 3, h = row & 7;
;         const bf16* src = c < 32 ? QL + ((size_t)(b * 8 + s) * 2048 + h * 256 + c * 8) : Q + ((size_t)(NPR + b * 8 + s) * QW + h * 96 + 64 + (c - 32) * 8);
;         *(LAS v4u*)(lds + QIMG + row * PB + c * 16) = *(const v4u*)src; }
.Lq1_join:
	s_or_b64 exec, exec, s[58:59]
	global_load_dwordx4 v[218:221], v[14:15], off
	s_movk_i32 s21, 0x6ff
	v_lshl_add_u32 v243, v7, 4, v1
	v_add_u32_e32 v7, 0x200, v4
	v_cmp_lt_i32_e32 vcc, s21, v4
	v_add_u32_e32 v1, 0x2000, v1
	v_add_u32_e32 v10, 0x1000, v10
	s_or_b64 s[56:57], vcc, s[56:57]
	v_mov_b32_e32 v4, v7

; #define LAS __attribute__((address_space(3)))
; __device__ __forceinline__ void unit(int b, int sp, const float* cache_lat, const float* cache_kr, const int* page_table, const bf16* QL, const bf16* Q, float* PO, float* PML, LAS unsigned char* lds, const int wid) {
;     ...
;     for (int idx = tid; idx < 64 * 36; idx += NWAVES * 64) { const int row = idx / 36, c = idx - row * 36, s = row >> 3, h = row & 7;
;         const bf16* src = c < 32 ? QL + ((size_t)(b * 8 + s) * 2048 + h * 256 + c * 8) : Q + ((size_t)(NPR + b * 8 + s) * QW + h * 96 + 64 + (c - 32) * 8);
;         *(LAS v4u*)(lds + QIMG + row * PB + c * 16) = *(const v4u*)src; }
.Lq2_join:
	s_or_b64 exec, exec, s[58:59]
	global_load_dwordx4 v[226:229], v[14:15], off
	s_movk_i32 s21, 0x6ff
	v_lshl_add_u32 v244, v7, 4, v1
	v_add_u32_e32 v7, 0x200, v4
	v_cmp_lt_i32_e32 vcc, s21, v4
	v_add_u32_e32 v1, 0x2000, v1
	v_add_u32_e32 v10, 0x1000, v10
	s_or_b64 s[56:57], vcc, s[56:57]
	v_mov_b32_e32 v4, v7

; #define LAS __attribute__((address_space(3)))
; __device__ __forceinline__ void unit(int b, int sp, const float* cache_lat, const float* cache_kr, const int* page_table, const bf16* QL, const bf16* Q, float* PO, float* PML, LAS unsigned char* lds, const int wid) {
;     ...
;     for (int idx = tid; idx < 64 * 36; idx += NWAVES * 64) { const int row = idx / 36, c = idx - row * 36, s = row >> 3, h = row & 7;
;         const bf16* src = c < 32 ? QL + ((size_t)(b * 8 + s) * 2048 + h * 256 + c * 8) : Q + ((size_t)(NPR + b * 8 + s) * QW + h * 96 + 64 + (c - 32) * 8);
;         *(LAS v4u*)(lds + QIMG + row * PB + c * 16) = *(const v4u*)src; }
.Lq3_join:
	s_or_b64 exec, exec, s[58:59]
	global_load_dwordx4 v[230:233], v[14:15], off
	s_movk_i32 s21, 0x6ff
	v_lshl_add_u32 v245, v7, 4, v1
	v_add_u32_e32 v7, 0x200, v4
	v_cmp_lt_i32_e32 vcc, s21, v4
	v_add_u32_e32 v1, 0x2000, v1
	v_add_u32_e32 v10, 0x1000, v10
	s_or_b64 s[56:57], vcc, s[56:57]
	v_mov_b32_e32 v4, v7
	s_andn2_b64 exec, exec, s[56:57]
	s_cbranch_execz .Lq_write4

; #define LAS __attribute__((address_space(3)))
; __device__ __forceinline__ void unit(int b, int sp, const float* cache_lat, const float* cache_kr, const int* page_table, const bf16* QL, const bf16* Q, float* PO, float* PML, LAS unsigned char* lds, const int wid) {
;     ...
;     for (int idx = tid; idx < 64 * 36; idx += NWAVES * 64) { const int row = idx / 36, c = idx - row * 36, s = row >> 3, h = row & 7;
;         const bf16* src = c < 32 ? QL + ((size_t)(b * 8 + s) * 2048 + h * 256 + c * 8) : Q + ((size_t)(NPR + b * 8 + s) * QW + h * 96 + 64 + (c - 32) * 8);
;         *(LAS v4u*)(lds + QIMG + row * PB + c * 16) = *(const v4u*)src; }
.Lq4_join:
	s_or_b64 exec, exec, s[58:59]
	global_load_dwordx4 v[238:241], v[14:15], off
	s_movk_i32 s21, 0x6ff
	v_lshl_add_u32 v246, v7, 4, v1
	v_add_u32_e32 v7, 0x200, v4
	v_cmp_lt_i32_e32 vcc, s21, v4
	v_add_u32_e32 v1, 0x2000, v1
	v_add_u32_e32 v10, 0x1000, v10
	s_or_b64 s[56:57], vcc, s[56:57]
	v_mov_b32_e32 v4, v7
	s_waitcnt vmcnt(0)
	ds_write_b128 v242, v[214:217]
	ds_write_b128 v243, v[218:221]
	ds_write_b128 v244, v[226:229]
	ds_write_b128 v245, v[230:233]
	ds_write_b128 v246, v[238:241]
	s_branch .LBB0_1040
.Lq_write4:
	s_or_b64 exec, exec, s[54:55]
	s_waitcnt vmcnt(0)
	ds_write_b128 v242, v[214:217]
	ds_write_b128 v243, v[218:221]
	ds_write_b128 v244, v[226:229]
	ds_write_b128 v245, v[230:233]
